# attention fast loops: second-half K/V fragments prefetched from LDS during the first half's tail (cross-body prefetch), on top of early reads
# baseline (speedup 1.0000x reference)
; #define MFMA32(a, b, c) __builtin_amdgcn_mfma_f32_32x32x16_bf16((a), (b), (c), 0, 0, 0)
; DI float fadd1(float a, float b) { float r; asm("v_add_f32 %0, %1, %2" : "=v"(r) : "v"(a), "v"(b)); return r; }
; template <int NKS>
; DI void attn_tile(const Params& p, int layer, int seq, int slot, int qt, char* smem, bool wr = true) {
;     ...
;       auto kb_body = [&](int kb) {
;         bf16x8 kf[NKS];
; #pragma unroll
;         for (int ks = 0; ks < NKS; ++ks) kf[ks] = *(const bf16x8*)(sK + swz(32 * kb + r, 2 * (ks0 + ks) + h));
;         bf16x8 pk[2][2];
; #pragma unroll
;         for (int qb = 0; qb < 2; ++qb) {
;           f32x16 st;
; #pragma unroll
;           for (int i = 0; i < 16; ++i) st[i] = SUB ? ncb[qb] : 0.f;
; #pragma unroll
;           for (int ks = 0; ks < NKS; ++ks) st = MFMA32(kf[ks], qf[qb][ks], st);
;           if constexpr (SUB) {
;             float ls = 0.f;
; #pragma unroll
;             for (int i = 0; i < 16; ++i) { float e = __builtin_amdgcn_exp2f(st[i]); st[i] = e; ls = fadd1(ls, e); }
;             lsum[qb] += ls;
;             pk[qb][0] = pack8(st, 0); pk[qb][1] = pack8(st, 1);
;           } else {
; #pragma unroll
;             for (int i = 0; i < 16; ++i) st[i] = __builtin_amdgcn_exp2f(st[i]);
;             pk[qb][0] = pack8(st, 0); pk[qb][1] = pack8(st, 1);
;             ls4[qb] = __builtin_amdgcn_mfma_f32_16x16x32_bf16(selA, pk[qb][0], ls4[qb], 0, 0, 0);
;             ls4[qb] = __builtin_amdgcn_mfma_f32_16x16x32_bf16(selA, pk[qb][1], ls4[qb], 0, 0, 0);
;           }
;         }
; #pragma unroll
;         for (int eb = 0; eb < 2; ++eb)
; #pragma unroll
;           for (int s2 = 0; s2 < 2; ++s2) {
;             bf16x8 vf = *(const bf16x8*)(sV + swz(32 * eb + r, 4 * kb + 2 * s2 + h));
; #pragma unroll
;             for (int qb = 0; qb < 2; ++qb) O[qb][eb] = MFMA32(vf, pk[qb][s2], O[qb][eb]);
;           }
;       };
.LBB0_639:
.LBB0_640:
	s_waitcnt lgkmcnt(8)
	v_mfma_f32_32x32x16_bf16 v[112:127], v[192:195], v[132:135], 0
	v_mfma_f32_32x32x16_bf16 v[112:127], v[196:199], v[136:139], v[112:127]
	s_waitcnt lgkmcnt(6)
	v_mfma_f32_32x32x16_bf16 v[112:127], v[200:203], v[140:143], v[112:127]
	v_mfma_f32_32x32x16_bf16 v[112:127], v[204:207], v[144:147], v[112:127]
	v_mfma_f32_32x32x16_bf16 v[96:111], v[192:195], v[148:151], 0
	v_mfma_f32_32x32x16_bf16 v[96:111], v[196:199], v[152:155], v[96:111]
	v_mfma_f32_32x32x16_bf16 v[96:111], v[200:203], v[156:159], v[96:111]
	v_mfma_f32_32x32x16_bf16 v[96:111], v[204:207], v[160:163], v[96:111]
	ds_read_b128 v[192:195], v130 offset:16384
	ds_read_b128 v[196:199], v130 offset:20480
	ds_read_b128 v[200:203], v131 offset:16384
	ds_read_b128 v[204:207], v131 offset:20480
	s_waitcnt lgkmcnt(9)
	v_mfma_f32_32x32x16_bf16 v[64:79], v[208:211], v[132:135], 0
	s_nop 1
	v_exp_f32_e32 v112, v112
	v_exp_f32_e32 v113, v113
	v_exp_f32_e32 v114, v114
	v_exp_f32_e32 v115, v115
	v_cvt_pk_bf16_f32 v112, v112, v113
	v_cvt_pk_bf16_f32 v113, v114, v115
	s_waitcnt lgkmcnt(6)
	v_mfma_f32_32x32x16_bf16 v[64:79], v[212:215], v[136:139], v[64:79]
	v_exp_f32_e32 v116, v116
	v_exp_f32_e32 v117, v117
	v_exp_f32_e32 v118, v118
	v_exp_f32_e32 v119, v119
	v_cvt_pk_bf16_f32 v114, v116, v117
	v_cvt_pk_bf16_f32 v115, v118, v119
	v_mfma_f32_32x32x16_bf16 v[64:79], v[216:219], v[140:143], v[64:79]
	v_exp_f32_e32 v120, v120
	v_exp_f32_e32 v121, v121
	v_exp_f32_e32 v122, v122
	v_exp_f32_e32 v123, v123
	v_cvt_pk_bf16_f32 v116, v120, v121
	v_cvt_pk_bf16_f32 v117, v122, v123
	v_mfma_f32_32x32x16_bf16 v[64:79], v[220:223], v[144:147], v[64:79]
	s_waitcnt lgkmcnt(4)
	v_mfma_f32_32x32x16_bf16 v[48:63], v[224:227], v[112:115], v[48:63]
	v_exp_f32_e32 v124, v124
	v_exp_f32_e32 v125, v125
	v_exp_f32_e32 v126, v126
	v_exp_f32_e32 v127, v127
	v_cvt_pk_bf16_f32 v118, v124, v125
	v_cvt_pk_bf16_f32 v119, v126, v127
	v_mfma_f32_32x32x16_bf16 v[80:95], v[208:211], v[148:151], 0
	v_mfma_f32_32x32x16_bf16 v[32:47], v[228:231], v[112:115], v[32:47]
	v_exp_f32_e32 v96, v96
	v_exp_f32_e32 v97, v97
	v_exp_f32_e32 v98, v98
	v_exp_f32_e32 v99, v99
	v_cvt_pk_bf16_f32 v96, v96, v97
	v_cvt_pk_bf16_f32 v97, v98, v99
	v_mfma_f32_16x16x32_bf16 v[164:167], v[172:175], v[112:115], v[164:167]
	v_mfma_f32_32x32x16_bf16 v[80:95], v[212:215], v[152:155], v[80:95]
	v_exp_f32_e32 v100, v100
	v_exp_f32_e32 v101, v101
	v_exp_f32_e32 v102, v102
	v_exp_f32_e32 v103, v103
	v_cvt_pk_bf16_f32 v98, v100, v101
	v_cvt_pk_bf16_f32 v99, v102, v103
	v_mfma_f32_32x32x16_bf16 v[80:95], v[216:219], v[156:159], v[80:95]
	s_waitcnt lgkmcnt(2)
	v_mfma_f32_32x32x16_bf16 v[48:63], v[192:195], v[116:119], v[48:63]
	v_exp_f32_e32 v104, v104
	v_exp_f32_e32 v105, v105
	v_exp_f32_e32 v106, v106
	v_exp_f32_e32 v107, v107
	v_cvt_pk_bf16_f32 v100, v104, v105
	v_cvt_pk_bf16_f32 v101, v106, v107
	v_mfma_f32_32x32x16_bf16 v[32:47], v[196:199], v[116:119], v[32:47]
	v_mfma_f32_16x16x32_bf16 v[164:167], v[172:175], v[116:119], v[164:167]
	v_exp_f32_e32 v108, v108
	v_exp_f32_e32 v109, v109
	v_exp_f32_e32 v110, v110
	v_exp_f32_e32 v111, v111
	v_cvt_pk_bf16_f32 v102, v108, v109
	v_cvt_pk_bf16_f32 v103, v110, v111
	v_mfma_f32_32x32x16_bf16 v[80:95], v[220:223], v[160:163], v[80:95]
	ds_read_b128 v[208:211], v191 offset:16384
	ds_read_b128 v[212:215], v191 offset:20480
	v_mfma_f32_32x32x16_bf16 v[16:31], v[224:227], v[96:99], v[16:31]
	v_exp_f32_e32 v64, v64
	v_exp_f32_e32 v65, v65
	v_exp_f32_e32 v66, v66
	v_exp_f32_e32 v67, v67
	v_cvt_pk_bf16_f32 v64, v64, v65
	v_cvt_pk_bf16_f32 v65, v66, v67
	v_mfma_f32_32x32x16_bf16 v[0:15], v[228:231], v[96:99], v[0:15]
	v_mfma_f32_16x16x32_bf16 v[168:171], v[172:175], v[96:99], v[168:171]
	v_exp_f32_e32 v68, v68
	v_exp_f32_e32 v69, v69
	v_exp_f32_e32 v70, v70
	v_exp_f32_e32 v71, v71
	v_cvt_pk_bf16_f32 v66, v68, v69
	v_cvt_pk_bf16_f32 v67, v70, v71
	v_mfma_f32_32x32x16_bf16 v[16:31], v[192:195], v[100:103], v[16:31]
	v_mfma_f32_32x32x16_bf16 v[0:15], v[196:199], v[100:103], v[0:15]
	ds_read_b128 v[216:219], v128 offset:8192
	ds_read_b128 v[220:223], v130 offset:8192
	ds_read_b128 v[224:227], v131 offset:8192
	ds_read_b128 v[228:231], v191 offset:8192
	ds_read_b128 v[192:195], v128 offset:12288
	ds_read_b128 v[196:199], v130 offset:12288
	v_exp_f32_e32 v72, v72
	v_exp_f32_e32 v73, v73
	v_exp_f32_e32 v74, v74
	v_exp_f32_e32 v75, v75
	v_cvt_pk_bf16_f32 v68, v72, v73
	v_cvt_pk_bf16_f32 v69, v74, v75
	v_mfma_f32_16x16x32_bf16 v[168:171], v[172:175], v[100:103], v[168:171]
	s_waitcnt lgkmcnt(8)
	v_mfma_f32_32x32x16_bf16 v[48:63], v[200:203], v[64:67], v[48:63]
	v_exp_f32_e32 v76, v76
	v_exp_f32_e32 v77, v77
	v_exp_f32_e32 v78, v78
	v_exp_f32_e32 v79, v79
	v_cvt_pk_bf16_f32 v70, v76, v77
	v_cvt_pk_bf16_f32 v71, v78, v79
	v_mfma_f32_32x32x16_bf16 v[32:47], v[204:207], v[64:67], v[32:47]
	v_mfma_f32_16x16x32_bf16 v[164:167], v[172:175], v[64:67], v[164:167]
	v_exp_f32_e32 v80, v80
	v_exp_f32_e32 v81, v81
	v_exp_f32_e32 v82, v82
	v_exp_f32_e32 v83, v83
	v_cvt_pk_bf16_f32 v80, v80, v81
	v_cvt_pk_bf16_f32 v81, v82, v83
	s_waitcnt lgkmcnt(6)
; #define MFMA32(a, b, c) __builtin_amdgcn_mfma_f32_32x32x16_bf16((a), (b), (c), 0, 0, 0)
; DI float fadd1(float a, float b) { float r; asm("v_add_f32 %0, %1, %2" : "=v"(r) : "v"(a), "v"(b)); return r; }
; template <int NKS>
; DI void attn_tile(const Params& p, int layer, int seq, int slot, int qt, char* smem, bool wr = true) {
;     ...
;       auto kb_body = [&](int kb) {
;         bf16x8 kf[NKS];
; #pragma unroll
;         for (int ks = 0; ks < NKS; ++ks) kf[ks] = *(const bf16x8*)(sK + swz(32 * kb + r, 2 * (ks0 + ks) + h));
;         bf16x8 pk[2][2];
; #pragma unroll
;         for (int qb = 0; qb < 2; ++qb) {
;           f32x16 st;
; #pragma unroll
;           for (int i = 0; i < 16; ++i) st[i] = SUB ? ncb[qb] : 0.f;
; #pragma unroll
;           for (int ks = 0; ks < NKS; ++ks) st = MFMA32(kf[ks], qf[qb][ks], st);
;           if constexpr (SUB) {
;             float ls = 0.f;
; #pragma unroll
;             for (int i = 0; i < 16; ++i) { float e = __builtin_amdgcn_exp2f(st[i]); st[i] = e; ls = fadd1(ls, e); }
;             lsum[qb] += ls;
;             pk[qb][0] = pack8(st, 0); pk[qb][1] = pack8(st, 1);
;           } else {
; #pragma unroll
;             for (int i = 0; i < 16; ++i) st[i] = __builtin_amdgcn_exp2f(st[i]);
;             pk[qb][0] = pack8(st, 0); pk[qb][1] = pack8(st, 1);
;             ls4[qb] = __builtin_amdgcn_mfma_f32_16x16x32_bf16(selA, pk[qb][0], ls4[qb], 0, 0, 0);
;             ls4[qb] = __builtin_amdgcn_mfma_f32_16x16x32_bf16(selA, pk[qb][1], ls4[qb], 0, 0, 0);
;           }
;         }
; #pragma unroll
;         for (int eb = 0; eb < 2; ++eb)
; #pragma unroll
;           for (int s2 = 0; s2 < 2; ++s2) {
;             bf16x8 vf = *(const bf16x8*)(sV + swz(32 * eb + r, 4 * kb + 2 * s2 + h));
; #pragma unroll
;             for (int qb = 0; qb < 2; ++qb) O[qb][eb] = MFMA32(vf, pk[qb][s2], O[qb][eb]);
;           }
;       };
	v_mfma_f32_32x32x16_bf16 v[48:63], v[208:211], v[68:71], v[48:63]
	v_exp_f32_e32 v84, v84
	v_exp_f32_e32 v85, v85
	v_exp_f32_e32 v86, v86
	v_exp_f32_e32 v87, v87
	v_cvt_pk_bf16_f32 v82, v84, v85
	v_cvt_pk_bf16_f32 v83, v86, v87
	v_mfma_f32_32x32x16_bf16 v[32:47], v[212:215], v[68:71], v[32:47]
	v_mfma_f32_16x16x32_bf16 v[164:167], v[172:175], v[68:71], v[164:167]
	v_exp_f32_e32 v88, v88
	v_exp_f32_e32 v89, v89
	v_exp_f32_e32 v90, v90
	v_exp_f32_e32 v91, v91
	v_cvt_pk_bf16_f32 v84, v88, v89
	v_cvt_pk_bf16_f32 v85, v90, v91
	v_mfma_f32_32x32x16_bf16 v[16:31], v[200:203], v[80:83], v[16:31]
	v_exp_f32_e32 v92, v92
	v_exp_f32_e32 v93, v93
	v_exp_f32_e32 v94, v94
	v_exp_f32_e32 v95, v95
	v_cvt_pk_bf16_f32 v86, v92, v93
	v_cvt_pk_bf16_f32 v87, v94, v95
	v_mfma_f32_32x32x16_bf16 v[0:15], v[204:207], v[80:83], v[0:15]
	ds_read_b128 v[200:203], v131 offset:12288
	ds_read_b128 v[204:207], v191 offset:12288
	v_mfma_f32_16x16x32_bf16 v[168:171], v[172:175], v[80:83], v[168:171]
	v_mfma_f32_32x32x16_bf16 v[16:31], v[208:211], v[84:87], v[16:31]
	v_mfma_f32_32x32x16_bf16 v[0:15], v[212:215], v[84:87], v[0:15]
	v_mfma_f32_16x16x32_bf16 v[168:171], v[172:175], v[84:87], v[168:171]
	ds_read_b128 v[208:211], v128 offset:24576
	ds_read_b128 v[212:215], v128 offset:28672
	s_waitcnt lgkmcnt(8)
	v_mfma_f32_32x32x16_bf16 v[112:127], v[216:219], v[132:135], 0
	v_mfma_f32_32x32x16_bf16 v[112:127], v[220:223], v[136:139], v[112:127]
	s_waitcnt lgkmcnt(6)
	v_mfma_f32_32x32x16_bf16 v[112:127], v[224:227], v[140:143], v[112:127]
	v_mfma_f32_32x32x16_bf16 v[112:127], v[228:231], v[144:147], v[112:127]
	v_mfma_f32_32x32x16_bf16 v[96:111], v[216:219], v[148:151], 0
	v_mfma_f32_32x32x16_bf16 v[96:111], v[220:223], v[152:155], v[96:111]
	v_mfma_f32_32x32x16_bf16 v[96:111], v[224:227], v[156:159], v[96:111]
	v_mfma_f32_32x32x16_bf16 v[96:111], v[228:231], v[160:163], v[96:111]
	ds_read_b128 v[216:219], v130 offset:24576
	ds_read_b128 v[220:223], v130 offset:28672
	ds_read_b128 v[224:227], v131 offset:24576
	ds_read_b128 v[228:231], v131 offset:28672
	s_waitcnt lgkmcnt(9)
	v_mfma_f32_32x32x16_bf16 v[64:79], v[192:195], v[132:135], 0
	s_nop 1
	v_exp_f32_e32 v112, v112
	v_exp_f32_e32 v113, v113
	v_exp_f32_e32 v114, v114
	v_exp_f32_e32 v115, v115
	v_cvt_pk_bf16_f32 v112, v112, v113
	v_cvt_pk_bf16_f32 v113, v114, v115
	s_waitcnt lgkmcnt(6)
	v_mfma_f32_32x32x16_bf16 v[64:79], v[196:199], v[136:139], v[64:79]
	v_exp_f32_e32 v116, v116
	v_exp_f32_e32 v117, v117
	v_exp_f32_e32 v118, v118
	v_exp_f32_e32 v119, v119
	v_cvt_pk_bf16_f32 v114, v116, v117
	v_cvt_pk_bf16_f32 v115, v118, v119
	v_mfma_f32_32x32x16_bf16 v[64:79], v[200:203], v[140:143], v[64:79]
	v_exp_f32_e32 v120, v120
	v_exp_f32_e32 v121, v121
	v_exp_f32_e32 v122, v122
	v_exp_f32_e32 v123, v123
	v_cvt_pk_bf16_f32 v116, v120, v121
	v_cvt_pk_bf16_f32 v117, v122, v123
	v_mfma_f32_32x32x16_bf16 v[64:79], v[204:207], v[144:147], v[64:79]
	s_waitcnt lgkmcnt(4)
	v_mfma_f32_32x32x16_bf16 v[48:63], v[208:211], v[112:115], v[48:63]
	v_exp_f32_e32 v124, v124
	v_exp_f32_e32 v125, v125
	v_exp_f32_e32 v126, v126
	v_exp_f32_e32 v127, v127
	v_cvt_pk_bf16_f32 v118, v124, v125
	v_cvt_pk_bf16_f32 v119, v126, v127
	v_mfma_f32_32x32x16_bf16 v[80:95], v[192:195], v[148:151], 0
	v_mfma_f32_32x32x16_bf16 v[32:47], v[212:215], v[112:115], v[32:47]
	v_exp_f32_e32 v96, v96
	v_exp_f32_e32 v97, v97
	v_exp_f32_e32 v98, v98
	v_exp_f32_e32 v99, v99
	v_cvt_pk_bf16_f32 v96, v96, v97
	v_cvt_pk_bf16_f32 v97, v98, v99
	v_mfma_f32_16x16x32_bf16 v[164:167], v[172:175], v[112:115], v[164:167]
	v_mfma_f32_32x32x16_bf16 v[80:95], v[196:199], v[152:155], v[80:95]
	v_exp_f32_e32 v100, v100
	v_exp_f32_e32 v101, v101
	v_exp_f32_e32 v102, v102
	v_exp_f32_e32 v103, v103
	v_cvt_pk_bf16_f32 v98, v100, v101
	v_cvt_pk_bf16_f32 v99, v102, v103
	v_mfma_f32_32x32x16_bf16 v[80:95], v[200:203], v[156:159], v[80:95]
	s_waitcnt lgkmcnt(2)
; #define MFMA32(a, b, c) __builtin_amdgcn_mfma_f32_32x32x16_bf16((a), (b), (c), 0, 0, 0)
; DI float fadd1(float a, float b) { float r; asm("v_add_f32 %0, %1, %2" : "=v"(r) : "v"(a), "v"(b)); return r; }
; template <int NKS>
; DI void attn_tile(const Params& p, int layer, int seq, int slot, int qt, char* smem, bool wr = true) {
;     ...
;       auto kb_body = [&](int kb) {
;         bf16x8 kf[NKS];
; #pragma unroll
;         for (int ks = 0; ks < NKS; ++ks) kf[ks] = *(const bf16x8*)(sK + swz(32 * kb + r, 2 * (ks0 + ks) + h));
;         bf16x8 pk[2][2];
; #pragma unroll
;         for (int qb = 0; qb < 2; ++qb) {
;           f32x16 st;
; #pragma unroll
;           for (int i = 0; i < 16; ++i) st[i] = SUB ? ncb[qb] : 0.f;
; #pragma unroll
;           for (int ks = 0; ks < NKS; ++ks) st = MFMA32(kf[ks], qf[qb][ks], st);
;           if constexpr (SUB) {
;             float ls = 0.f;
; #pragma unroll
;             for (int i = 0; i < 16; ++i) { float e = __builtin_amdgcn_exp2f(st[i]); st[i] = e; ls = fadd1(ls, e); }
;             lsum[qb] += ls;
;             pk[qb][0] = pack8(st, 0); pk[qb][1] = pack8(st, 1);
;           } else {
; #pragma unroll
;             for (int i = 0; i < 16; ++i) st[i] = __builtin_amdgcn_exp2f(st[i]);
;             pk[qb][0] = pack8(st, 0); pk[qb][1] = pack8(st, 1);
;             ls4[qb] = __builtin_amdgcn_mfma_f32_16x16x32_bf16(selA, pk[qb][0], ls4[qb], 0, 0, 0);
;             ls4[qb] = __builtin_amdgcn_mfma_f32_16x16x32_bf16(selA, pk[qb][1], ls4[qb], 0, 0, 0);
;           }
;         }
; #pragma unroll
;         for (int eb = 0; eb < 2; ++eb)
; #pragma unroll
;           for (int s2 = 0; s2 < 2; ++s2) {
;             bf16x8 vf = *(const bf16x8*)(sV + swz(32 * eb + r, 4 * kb + 2 * s2 + h));
; #pragma unroll
;             for (int qb = 0; qb < 2; ++qb) O[qb][eb] = MFMA32(vf, pk[qb][s2], O[qb][eb]);
;           }
;       };
	v_mfma_f32_32x32x16_bf16 v[48:63], v[216:219], v[116:119], v[48:63]
	v_exp_f32_e32 v104, v104
	v_exp_f32_e32 v105, v105
	v_exp_f32_e32 v106, v106
	v_exp_f32_e32 v107, v107
	v_cvt_pk_bf16_f32 v100, v104, v105
	v_cvt_pk_bf16_f32 v101, v106, v107
	v_mfma_f32_32x32x16_bf16 v[32:47], v[220:223], v[116:119], v[32:47]
	v_mfma_f32_16x16x32_bf16 v[164:167], v[172:175], v[116:119], v[164:167]
	v_exp_f32_e32 v108, v108
	v_exp_f32_e32 v109, v109
	v_exp_f32_e32 v110, v110
	v_exp_f32_e32 v111, v111
	v_cvt_pk_bf16_f32 v102, v108, v109
	v_cvt_pk_bf16_f32 v103, v110, v111
	v_mfma_f32_32x32x16_bf16 v[80:95], v[204:207], v[160:163], v[80:95]
	ds_read_b128 v[192:195], v191 offset:24576
	ds_read_b128 v[196:199], v191 offset:28672
	v_mfma_f32_32x32x16_bf16 v[16:31], v[208:211], v[96:99], v[16:31]
	v_exp_f32_e32 v64, v64
	v_exp_f32_e32 v65, v65
	v_exp_f32_e32 v66, v66
	v_exp_f32_e32 v67, v67
	v_cvt_pk_bf16_f32 v64, v64, v65
	v_cvt_pk_bf16_f32 v65, v66, v67
	v_mfma_f32_32x32x16_bf16 v[0:15], v[212:215], v[96:99], v[0:15]
	v_mfma_f32_16x16x32_bf16 v[168:171], v[172:175], v[96:99], v[168:171]
	v_exp_f32_e32 v68, v68
	v_exp_f32_e32 v69, v69
	v_exp_f32_e32 v70, v70
	v_exp_f32_e32 v71, v71
	v_cvt_pk_bf16_f32 v66, v68, v69
	v_cvt_pk_bf16_f32 v67, v70, v71
	v_mfma_f32_32x32x16_bf16 v[16:31], v[216:219], v[100:103], v[16:31]
	v_mfma_f32_32x32x16_bf16 v[0:15], v[220:223], v[100:103], v[0:15]
	v_exp_f32_e32 v72, v72
	v_exp_f32_e32 v73, v73
	v_exp_f32_e32 v74, v74
	v_exp_f32_e32 v75, v75
	v_cvt_pk_bf16_f32 v68, v72, v73
	v_cvt_pk_bf16_f32 v69, v74, v75
	v_mfma_f32_16x16x32_bf16 v[168:171], v[172:175], v[100:103], v[168:171]
	s_waitcnt lgkmcnt(2)
	v_mfma_f32_32x32x16_bf16 v[48:63], v[224:227], v[64:67], v[48:63]
	v_exp_f32_e32 v76, v76
	v_exp_f32_e32 v77, v77
	v_exp_f32_e32 v78, v78
	v_exp_f32_e32 v79, v79
	v_cvt_pk_bf16_f32 v70, v76, v77
	v_cvt_pk_bf16_f32 v71, v78, v79
	v_mfma_f32_32x32x16_bf16 v[32:47], v[228:231], v[64:67], v[32:47]
	v_mfma_f32_16x16x32_bf16 v[164:167], v[172:175], v[64:67], v[164:167]
	v_exp_f32_e32 v80, v80
	v_exp_f32_e32 v81, v81
	v_exp_f32_e32 v82, v82
	v_exp_f32_e32 v83, v83
	v_cvt_pk_bf16_f32 v80, v80, v81
	v_cvt_pk_bf16_f32 v81, v82, v83
	s_waitcnt lgkmcnt(0)
	v_mfma_f32_32x32x16_bf16 v[48:63], v[192:195], v[68:71], v[48:63]
	v_exp_f32_e32 v84, v84
	v_exp_f32_e32 v85, v85
	v_exp_f32_e32 v86, v86
	v_exp_f32_e32 v87, v87
	v_cvt_pk_bf16_f32 v82, v84, v85
	v_cvt_pk_bf16_f32 v83, v86, v87
	v_mfma_f32_32x32x16_bf16 v[32:47], v[196:199], v[68:71], v[32:47]
	v_mfma_f32_16x16x32_bf16 v[164:167], v[172:175], v[68:71], v[164:167]
	v_exp_f32_e32 v88, v88
	v_exp_f32_e32 v89, v89
	v_exp_f32_e32 v90, v90
	v_exp_f32_e32 v91, v91
	v_cvt_pk_bf16_f32 v84, v88, v89
	v_cvt_pk_bf16_f32 v85, v90, v91
	v_mfma_f32_32x32x16_bf16 v[16:31], v[224:227], v[80:83], v[16:31]
	v_exp_f32_e32 v92, v92
	v_exp_f32_e32 v93, v93
	v_exp_f32_e32 v94, v94
	v_exp_f32_e32 v95, v95
	v_cvt_pk_bf16_f32 v86, v92, v93
	v_cvt_pk_bf16_f32 v87, v94, v95
	v_mfma_f32_32x32x16_bf16 v[0:15], v[228:231], v[80:83], v[0:15]
	v_mfma_f32_16x16x32_bf16 v[168:171], v[172:175], v[80:83], v[168:171]
	v_mfma_f32_32x32x16_bf16 v[16:31], v[192:195], v[84:87], v[16:31]
	v_mfma_f32_32x32x16_bf16 v[0:15], v[196:199], v[84:87], v[0:15]
	v_mfma_f32_16x16x32_bf16 v[168:171], v[172:175], v[84:87], v[168:171]

; template <int NKS>
; DI void attn_tile(const Params& p, int layer, int seq, int slot, int qt, char* smem, bool wr = true) {
;     ...
;     for (int kt = 0; kt < nkt; ++kt) {
;       asm volatile("s_waitcnt vmcnt(0)" ::: "memory");
;       __syncthreads();
;       if (kt + 1 < nkt) stage(kt + 1);
	s_cmp_eq_u32 s28, s25
	s_cbranch_scc1 .LBB0_643
	s_mov_b32 s29, s28
	s_branch .LBB0_637

; #define MFMA32(a, b, c) __builtin_amdgcn_mfma_f32_32x32x16_bf16((a), (b), (c), 0, 0, 0)
; DI float fadd1(float a, float b) { float r; asm("v_add_f32 %0, %1, %2" : "=v"(r) : "v"(a), "v"(b)); return r; }
; template <int NKS>
; DI void attn_tile(const Params& p, int layer, int seq, int slot, int qt, char* smem, bool wr = true) {
;     ...
;       auto kb_body = [&](int kb) {
;         bf16x8 kf[NKS];
; #pragma unroll
;         for (int ks = 0; ks < NKS; ++ks) kf[ks] = *(const bf16x8*)(sK + swz(32 * kb + r, 2 * (ks0 + ks) + h));
;         bf16x8 pk[2][2];
; #pragma unroll
;         for (int qb = 0; qb < 2; ++qb) {
;           f32x16 st;
; #pragma unroll
;           for (int i = 0; i < 16; ++i) st[i] = SUB ? ncb[qb] : 0.f;
; #pragma unroll
;           for (int ks = 0; ks < NKS; ++ks) st = MFMA32(kf[ks], qf[qb][ks], st);
;           if constexpr (SUB) {
;             float ls = 0.f;
; #pragma unroll
;             for (int i = 0; i < 16; ++i) { float e = __builtin_amdgcn_exp2f(st[i]); st[i] = e; ls = fadd1(ls, e); }
;             lsum[qb] += ls;
;             pk[qb][0] = pack8(st, 0); pk[qb][1] = pack8(st, 1);
;           } else {
; #pragma unroll
;             for (int i = 0; i < 16; ++i) st[i] = __builtin_amdgcn_exp2f(st[i]);
;             pk[qb][0] = pack8(st, 0); pk[qb][1] = pack8(st, 1);
;             ls4[qb] = __builtin_amdgcn_mfma_f32_16x16x32_bf16(selA, pk[qb][0], ls4[qb], 0, 0, 0);
;             ls4[qb] = __builtin_amdgcn_mfma_f32_16x16x32_bf16(selA, pk[qb][1], ls4[qb], 0, 0, 0);
;           }
;         }
; #pragma unroll
;         for (int eb = 0; eb < 2; ++eb)
; #pragma unroll
;           for (int s2 = 0; s2 < 2; ++s2) {
;             bf16x8 vf = *(const bf16x8*)(sV + swz(32 * eb + r, 4 * kb + 2 * s2 + h));
; #pragma unroll
;             for (int qb = 0; qb < 2; ++qb) O[qb][eb] = MFMA32(vf, pk[qb][s2], O[qb][eb]);
;           }
;       };
.LBB0_673:
.LBB0_674:
	s_waitcnt lgkmcnt(7)
	v_mfma_f32_32x32x16_bf16 v[112:127], v[180:183], v[132:135], 0
	v_mfma_f32_32x32x16_bf16 v[112:127], v[184:187], v[136:139], v[112:127]
	v_mfma_f32_32x32x16_bf16 v[96:111], v[180:183], v[140:143], 0
	v_mfma_f32_32x32x16_bf16 v[96:111], v[184:187], v[144:147], v[96:111]
	ds_read_b128 v[180:183], v189 offset:20480
	ds_read_b128 v[184:187], v190 offset:16384
	s_waitcnt lgkmcnt(7)
	v_mfma_f32_32x32x16_bf16 v[64:79], v[204:207], v[132:135], 0
	v_mfma_f32_32x32x16_bf16 v[64:79], v[208:211], v[136:139], v[64:79]
	s_nop 4
	v_exp_f32_e32 v112, v112
	v_exp_f32_e32 v113, v113
	v_exp_f32_e32 v114, v114
	v_exp_f32_e32 v115, v115
	v_cvt_pk_bf16_f32 v112, v112, v113
	v_cvt_pk_bf16_f32 v113, v114, v115
	v_mfma_f32_32x32x16_bf16 v[80:95], v[204:207], v[140:143], 0
	ds_read_b128 v[204:207], v190 offset:20480
	v_exp_f32_e32 v116, v116
	v_exp_f32_e32 v117, v117
	v_exp_f32_e32 v118, v118
	v_exp_f32_e32 v119, v119
	v_cvt_pk_bf16_f32 v114, v116, v117
	v_cvt_pk_bf16_f32 v115, v118, v119
	v_mfma_f32_32x32x16_bf16 v[80:95], v[208:211], v[144:147], v[80:95]
	v_exp_f32_e32 v120, v120
	v_exp_f32_e32 v121, v121
	v_exp_f32_e32 v122, v122
	v_exp_f32_e32 v123, v123
	v_cvt_pk_bf16_f32 v116, v120, v121
	v_cvt_pk_bf16_f32 v117, v122, v123
	s_waitcnt lgkmcnt(6)
	v_mfma_f32_32x32x16_bf16 v[48:63], v[212:215], v[112:115], v[48:63]
	v_exp_f32_e32 v124, v124
	v_exp_f32_e32 v125, v125
	v_exp_f32_e32 v126, v126
	v_exp_f32_e32 v127, v127
	v_cvt_pk_bf16_f32 v118, v124, v125
	v_cvt_pk_bf16_f32 v119, v126, v127
	v_mfma_f32_32x32x16_bf16 v[32:47], v[216:219], v[112:115], v[32:47]
	v_exp_f32_e32 v96, v96
	v_exp_f32_e32 v97, v97
	v_exp_f32_e32 v98, v98
	v_exp_f32_e32 v99, v99
	v_cvt_pk_bf16_f32 v96, v96, v97
	v_cvt_pk_bf16_f32 v97, v98, v99
	v_mfma_f32_16x16x32_bf16 v[148:151], v[156:159], v[112:115], v[148:151]
	s_waitcnt lgkmcnt(4)
	v_mfma_f32_32x32x16_bf16 v[48:63], v[220:223], v[116:119], v[48:63]
	v_exp_f32_e32 v100, v100
	v_exp_f32_e32 v101, v101
	v_exp_f32_e32 v102, v102
	v_exp_f32_e32 v103, v103
	v_cvt_pk_bf16_f32 v98, v100, v101
	v_cvt_pk_bf16_f32 v99, v102, v103
	v_mfma_f32_32x32x16_bf16 v[32:47], v[224:227], v[116:119], v[32:47]
	v_mfma_f32_16x16x32_bf16 v[148:151], v[156:159], v[116:119], v[148:151]
	v_exp_f32_e32 v104, v104
	v_exp_f32_e32 v105, v105
	v_exp_f32_e32 v106, v106
	v_exp_f32_e32 v107, v107
	v_cvt_pk_bf16_f32 v100, v104, v105
	v_cvt_pk_bf16_f32 v101, v106, v107
	v_mfma_f32_32x32x16_bf16 v[16:31], v[212:215], v[96:99], v[16:31]
	v_exp_f32_e32 v108, v108
	v_exp_f32_e32 v109, v109
	v_exp_f32_e32 v110, v110
	v_exp_f32_e32 v111, v111
	v_cvt_pk_bf16_f32 v102, v108, v109
	v_cvt_pk_bf16_f32 v103, v110, v111
	v_mfma_f32_32x32x16_bf16 v[0:15], v[216:219], v[96:99], v[0:15]
	v_mfma_f32_16x16x32_bf16 v[152:155], v[156:159], v[96:99], v[152:155]
	v_exp_f32_e32 v64, v64
	v_exp_f32_e32 v65, v65
	v_exp_f32_e32 v66, v66
	v_exp_f32_e32 v67, v67
	v_cvt_pk_bf16_f32 v64, v64, v65
	v_cvt_pk_bf16_f32 v65, v66, v67
	v_mfma_f32_32x32x16_bf16 v[16:31], v[220:223], v[100:103], v[16:31]
	v_mfma_f32_32x32x16_bf16 v[0:15], v[224:227], v[100:103], v[0:15]
	ds_read_b128 v[212:215], v128 offset:8192
	ds_read_b128 v[216:219], v130 offset:8192
	ds_read_b128 v[220:223], v128 offset:12288
	ds_read_b128 v[224:227], v130 offset:12288
	ds_read_b128 v[208:211], v131 offset:24576
	v_exp_f32_e32 v68, v68
	v_exp_f32_e32 v69, v69
	v_exp_f32_e32 v70, v70
	v_exp_f32_e32 v71, v71
	v_cvt_pk_bf16_f32 v66, v68, v69
	v_cvt_pk_bf16_f32 v67, v70, v71
	v_mfma_f32_16x16x32_bf16 v[152:155], v[156:159], v[100:103], v[152:155]
	s_waitcnt lgkmcnt(7)
	v_mfma_f32_32x32x16_bf16 v[48:63], v[228:231], v[64:67], v[48:63]
	v_exp_f32_e32 v72, v72
	v_exp_f32_e32 v73, v73
	v_exp_f32_e32 v74, v74
	v_exp_f32_e32 v75, v75
	v_cvt_pk_bf16_f32 v68, v72, v73
	v_cvt_pk_bf16_f32 v69, v74, v75
	v_mfma_f32_32x32x16_bf16 v[32:47], v[180:183], v[64:67], v[32:47]
	v_mfma_f32_16x16x32_bf16 v[148:151], v[156:159], v[64:67], v[148:151]
	v_exp_f32_e32 v76, v76
	v_exp_f32_e32 v77, v77
	v_exp_f32_e32 v78, v78
	v_exp_f32_e32 v79, v79
	v_cvt_pk_bf16_f32 v70, v76, v77
	v_cvt_pk_bf16_f32 v71, v78, v79
	s_waitcnt lgkmcnt(5)
	s_nop 0
	v_mfma_f32_32x32x16_bf16 v[48:63], v[184:187], v[68:71], v[48:63]
	v_exp_f32_e32 v80, v80
	v_exp_f32_e32 v81, v81
	v_exp_f32_e32 v82, v82
	v_exp_f32_e32 v83, v83
	v_cvt_pk_bf16_f32 v80, v80, v81
	v_cvt_pk_bf16_f32 v81, v82, v83
	v_mfma_f32_32x32x16_bf16 v[32:47], v[204:207], v[68:71], v[32:47]
	v_mfma_f32_16x16x32_bf16 v[148:151], v[156:159], v[68:71], v[148:151]
	v_exp_f32_e32 v84, v84
	v_exp_f32_e32 v85, v85
	v_exp_f32_e32 v86, v86
	v_exp_f32_e32 v87, v87
	v_cvt_pk_bf16_f32 v82, v84, v85
	v_cvt_pk_bf16_f32 v83, v86, v87
	v_exp_f32_e32 v88, v88
	v_exp_f32_e32 v89, v89
	v_exp_f32_e32 v90, v90
	v_exp_f32_e32 v91, v91
	v_cvt_pk_bf16_f32 v84, v88, v89
	v_cvt_pk_bf16_f32 v85, v90, v91
	v_mfma_f32_32x32x16_bf16 v[16:31], v[228:231], v[80:83], v[16:31]
	ds_read_b128 v[228:231], v131 offset:28672
	v_exp_f32_e32 v92, v92
	v_exp_f32_e32 v93, v93
	v_exp_f32_e32 v94, v94
	v_exp_f32_e32 v95, v95
	v_cvt_pk_bf16_f32 v86, v92, v93
	v_cvt_pk_bf16_f32 v87, v94, v95
	v_mfma_f32_32x32x16_bf16 v[0:15], v[180:183], v[80:83], v[0:15]
	ds_read_b128 v[180:183], v188 offset:24576
	v_mfma_f32_16x16x32_bf16 v[152:155], v[156:159], v[80:83], v[152:155]
	v_mfma_f32_32x32x16_bf16 v[16:31], v[184:187], v[84:87], v[16:31]
	ds_read_b128 v[184:187], v188 offset:28672
	v_mfma_f32_32x32x16_bf16 v[0:15], v[204:207], v[84:87], v[0:15]
	v_mfma_f32_16x16x32_bf16 v[152:155], v[156:159], v[84:87], v[152:155]
	ds_read_b128 v[204:207], v189 offset:24576
	s_waitcnt lgkmcnt(7)
; #define MFMA32(a, b, c) __builtin_amdgcn_mfma_f32_32x32x16_bf16((a), (b), (c), 0, 0, 0)
; DI float fadd1(float a, float b) { float r; asm("v_add_f32 %0, %1, %2" : "=v"(r) : "v"(a), "v"(b)); return r; }
; template <int NKS>
; DI void attn_tile(const Params& p, int layer, int seq, int slot, int qt, char* smem, bool wr = true) {
;     ...
;       auto kb_body = [&](int kb) {
;         bf16x8 kf[NKS];
; #pragma unroll
;         for (int ks = 0; ks < NKS; ++ks) kf[ks] = *(const bf16x8*)(sK + swz(32 * kb + r, 2 * (ks0 + ks) + h));
;         bf16x8 pk[2][2];
; #pragma unroll
;         for (int qb = 0; qb < 2; ++qb) {
;           f32x16 st;
; #pragma unroll
;           for (int i = 0; i < 16; ++i) st[i] = SUB ? ncb[qb] : 0.f;
; #pragma unroll
;           for (int ks = 0; ks < NKS; ++ks) st = MFMA32(kf[ks], qf[qb][ks], st);
;           if constexpr (SUB) {
;             float ls = 0.f;
; #pragma unroll
;             for (int i = 0; i < 16; ++i) { float e = __builtin_amdgcn_exp2f(st[i]); st[i] = e; ls = fadd1(ls, e); }
;             lsum[qb] += ls;
;             pk[qb][0] = pack8(st, 0); pk[qb][1] = pack8(st, 1);
;           } else {
; #pragma unroll
;             for (int i = 0; i < 16; ++i) st[i] = __builtin_amdgcn_exp2f(st[i]);
;             pk[qb][0] = pack8(st, 0); pk[qb][1] = pack8(st, 1);
;             ls4[qb] = __builtin_amdgcn_mfma_f32_16x16x32_bf16(selA, pk[qb][0], ls4[qb], 0, 0, 0);
;             ls4[qb] = __builtin_amdgcn_mfma_f32_16x16x32_bf16(selA, pk[qb][1], ls4[qb], 0, 0, 0);
;           }
;         }
; #pragma unroll
;         for (int eb = 0; eb < 2; ++eb)
; #pragma unroll
;           for (int s2 = 0; s2 < 2; ++s2) {
;             bf16x8 vf = *(const bf16x8*)(sV + swz(32 * eb + r, 4 * kb + 2 * s2 + h));
; #pragma unroll
;             for (int qb = 0; qb < 2; ++qb) O[qb][eb] = MFMA32(vf, pk[qb][s2], O[qb][eb]);
;           }
;       };
	v_mfma_f32_32x32x16_bf16 v[112:127], v[212:215], v[132:135], 0
	v_mfma_f32_32x32x16_bf16 v[112:127], v[216:219], v[136:139], v[112:127]
	v_mfma_f32_32x32x16_bf16 v[96:111], v[212:215], v[140:143], 0
	v_mfma_f32_32x32x16_bf16 v[96:111], v[216:219], v[144:147], v[96:111]
	ds_read_b128 v[212:215], v189 offset:28672
	ds_read_b128 v[216:219], v190 offset:24576
	s_waitcnt lgkmcnt(7)
	v_mfma_f32_32x32x16_bf16 v[64:79], v[220:223], v[132:135], 0
	v_mfma_f32_32x32x16_bf16 v[64:79], v[224:227], v[136:139], v[64:79]
	s_nop 4
	v_exp_f32_e32 v112, v112
	v_exp_f32_e32 v113, v113
	v_exp_f32_e32 v114, v114
	v_exp_f32_e32 v115, v115
	v_cvt_pk_bf16_f32 v112, v112, v113
	v_cvt_pk_bf16_f32 v113, v114, v115
	v_mfma_f32_32x32x16_bf16 v[80:95], v[220:223], v[140:143], 0
	ds_read_b128 v[220:223], v190 offset:28672
	v_exp_f32_e32 v116, v116
	v_exp_f32_e32 v117, v117
	v_exp_f32_e32 v118, v118
	v_exp_f32_e32 v119, v119
	v_cvt_pk_bf16_f32 v114, v116, v117
	v_cvt_pk_bf16_f32 v115, v118, v119
	v_mfma_f32_32x32x16_bf16 v[80:95], v[224:227], v[144:147], v[80:95]
	v_exp_f32_e32 v120, v120
	v_exp_f32_e32 v121, v121
	v_exp_f32_e32 v122, v122
	v_exp_f32_e32 v123, v123
	v_cvt_pk_bf16_f32 v116, v120, v121
	v_cvt_pk_bf16_f32 v117, v122, v123
	s_waitcnt lgkmcnt(6)
	v_mfma_f32_32x32x16_bf16 v[48:63], v[208:211], v[112:115], v[48:63]
	v_exp_f32_e32 v124, v124
	v_exp_f32_e32 v125, v125
	v_exp_f32_e32 v126, v126
	v_exp_f32_e32 v127, v127
	v_cvt_pk_bf16_f32 v118, v124, v125
	v_cvt_pk_bf16_f32 v119, v126, v127
	v_mfma_f32_32x32x16_bf16 v[32:47], v[228:231], v[112:115], v[32:47]
	v_exp_f32_e32 v96, v96
	v_exp_f32_e32 v97, v97
	v_exp_f32_e32 v98, v98
	v_exp_f32_e32 v99, v99
	v_cvt_pk_bf16_f32 v96, v96, v97
	v_cvt_pk_bf16_f32 v97, v98, v99
	v_mfma_f32_16x16x32_bf16 v[148:151], v[156:159], v[112:115], v[148:151]
	s_waitcnt lgkmcnt(4)
	v_mfma_f32_32x32x16_bf16 v[48:63], v[180:183], v[116:119], v[48:63]
	v_exp_f32_e32 v100, v100
	v_exp_f32_e32 v101, v101
	v_exp_f32_e32 v102, v102
	v_exp_f32_e32 v103, v103
	v_cvt_pk_bf16_f32 v98, v100, v101
	v_cvt_pk_bf16_f32 v99, v102, v103
	v_mfma_f32_32x32x16_bf16 v[32:47], v[184:187], v[116:119], v[32:47]
	v_mfma_f32_16x16x32_bf16 v[148:151], v[156:159], v[116:119], v[148:151]
	v_exp_f32_e32 v104, v104
	v_exp_f32_e32 v105, v105
	v_exp_f32_e32 v106, v106
	v_exp_f32_e32 v107, v107
	v_cvt_pk_bf16_f32 v100, v104, v105
	v_cvt_pk_bf16_f32 v101, v106, v107
	v_mfma_f32_32x32x16_bf16 v[16:31], v[208:211], v[96:99], v[16:31]
	v_exp_f32_e32 v108, v108
	v_exp_f32_e32 v109, v109
	v_exp_f32_e32 v110, v110
	v_exp_f32_e32 v111, v111
	v_cvt_pk_bf16_f32 v102, v108, v109
	v_cvt_pk_bf16_f32 v103, v110, v111
	v_mfma_f32_32x32x16_bf16 v[0:15], v[228:231], v[96:99], v[0:15]
	v_mfma_f32_16x16x32_bf16 v[152:155], v[156:159], v[96:99], v[152:155]
	v_exp_f32_e32 v64, v64
	v_exp_f32_e32 v65, v65
	v_exp_f32_e32 v66, v66
	v_exp_f32_e32 v67, v67
	v_cvt_pk_bf16_f32 v64, v64, v65
	v_cvt_pk_bf16_f32 v65, v66, v67
	v_mfma_f32_32x32x16_bf16 v[16:31], v[180:183], v[100:103], v[16:31]
	v_mfma_f32_32x32x16_bf16 v[0:15], v[184:187], v[100:103], v[0:15]
	v_exp_f32_e32 v68, v68
	v_exp_f32_e32 v69, v69
	v_exp_f32_e32 v70, v70
	v_exp_f32_e32 v71, v71
	v_cvt_pk_bf16_f32 v66, v68, v69
	v_cvt_pk_bf16_f32 v67, v70, v71
	v_mfma_f32_16x16x32_bf16 v[152:155], v[156:159], v[100:103], v[152:155]
	s_waitcnt lgkmcnt(2)
	v_mfma_f32_32x32x16_bf16 v[48:63], v[204:207], v[64:67], v[48:63]
	v_exp_f32_e32 v72, v72
	v_exp_f32_e32 v73, v73
	v_exp_f32_e32 v74, v74
	v_exp_f32_e32 v75, v75
	v_cvt_pk_bf16_f32 v68, v72, v73
	v_cvt_pk_bf16_f32 v69, v74, v75
	v_mfma_f32_32x32x16_bf16 v[32:47], v[212:215], v[64:67], v[32:47]
	v_mfma_f32_16x16x32_bf16 v[148:151], v[156:159], v[64:67], v[148:151]
	v_exp_f32_e32 v76, v76
	v_exp_f32_e32 v77, v77
	v_exp_f32_e32 v78, v78
	v_exp_f32_e32 v79, v79
	v_cvt_pk_bf16_f32 v70, v76, v77
	v_cvt_pk_bf16_f32 v71, v78, v79
	s_waitcnt lgkmcnt(0)
	s_nop 0
	v_mfma_f32_32x32x16_bf16 v[48:63], v[216:219], v[68:71], v[48:63]
	v_exp_f32_e32 v80, v80
	v_exp_f32_e32 v81, v81
	v_exp_f32_e32 v82, v82
	v_exp_f32_e32 v83, v83
	v_cvt_pk_bf16_f32 v80, v80, v81
	v_cvt_pk_bf16_f32 v81, v82, v83
	v_mfma_f32_32x32x16_bf16 v[32:47], v[220:223], v[68:71], v[32:47]
	v_mfma_f32_16x16x32_bf16 v[148:151], v[156:159], v[68:71], v[148:151]
	v_exp_f32_e32 v84, v84
	v_exp_f32_e32 v85, v85
	v_exp_f32_e32 v86, v86
	v_exp_f32_e32 v87, v87
	v_cvt_pk_bf16_f32 v82, v84, v85
	v_cvt_pk_bf16_f32 v83, v86, v87
	v_exp_f32_e32 v88, v88
	v_exp_f32_e32 v89, v89
	v_exp_f32_e32 v90, v90
	v_exp_f32_e32 v91, v91
	v_cvt_pk_bf16_f32 v84, v88, v89
	v_cvt_pk_bf16_f32 v85, v90, v91
	v_mfma_f32_32x32x16_bf16 v[16:31], v[204:207], v[80:83], v[16:31]
	v_exp_f32_e32 v92, v92
	v_exp_f32_e32 v93, v93
	v_exp_f32_e32 v94, v94
	v_exp_f32_e32 v95, v95
	v_cvt_pk_bf16_f32 v86, v92, v93
	v_cvt_pk_bf16_f32 v87, v94, v95
	v_mfma_f32_32x32x16_bf16 v[0:15], v[212:215], v[80:83], v[0:15]
	v_mfma_f32_16x16x32_bf16 v[152:155], v[156:159], v[80:83], v[152:155]
	v_mfma_f32_32x32x16_bf16 v[16:31], v[216:219], v[84:87], v[16:31]
	v_mfma_f32_32x32x16_bf16 v[0:15], v[220:223], v[84:87], v[0:15]
	v_mfma_f32_16x16x32_bf16 v[152:155], v[156:159], v[84:87], v[152:155]

; template <int NKS>
; DI void attn_tile(const Params& p, int layer, int seq, int slot, int qt, char* smem, bool wr = true) {
;     ...
;     for (int kt = 0; kt < nkt; ++kt) {
;       asm volatile("s_waitcnt vmcnt(0)" ::: "memory");
;       __syncthreads();
;       if (kt + 1 < nkt) stage(kt + 1);
	s_cmp_eq_u32 s36, s31
	s_cbranch_scc1 .LBB0_677
	s_mov_b32 s37, s36
	s_branch .LBB0_671
